# row-sum selector MFMAs of the dense loops issued after the end-of-iteration barrier (cover next tile's K read latency; barrier reached earlier)
# speedup vs baseline: 1.0020x; 1.0019x over previous
; #define MFMA(a, b, c) __builtin_amdgcn_mfma_f32_32x32x16_bf16((a), (b), (c), 0, 0, 0)
; DI unsigned pk2(float a, float b) { f32x2 v = {a, b}; bf16x2_t r = __builtin_convertvector(v, bf16x2_t); return __builtin_bit_cast(unsigned, r); }
; template <int DQK, bool BAND, int QT> ...
;     ...
;         const float mc = -m[qt] * cc;
;         float ls = 0.f;
; #pragma unroll
;         for (int a = 0; a < 2; ++a) {
; #pragma unroll
;           for (int r = 0; r < 16; ++r) { const float pv = __builtin_amdgcn_exp2f(fmaf(s[a][qt][r], cc, mc)); s[a][qt][r] = pv; ls += pv; }
; #pragma unroll
;           for (int s2 = 0; s2 < 2; ++s2) {
;             u32x4 pk;
;             pk.x = pk2(s[a][qt][8 * s2 + 0], s[a][qt][8 * s2 + 1]);
;             pk.y = pk2(s[a][qt][8 * s2 + 2], s[a][qt][8 * s2 + 3]);
;             pk.z = pk2(s[a][qt][8 * s2 + 4], s[a][qt][8 * s2 + 5]);
;             pk.w = pk2(s[a][qt][8 * s2 + 6], s[a][qt][8 * s2 + 7]);
;             pf[qt][a * 2 + s2] = __builtin_bit_cast(bf16x8, pk);
;           }
;         }
;         l[qt] += ls;
;       }
;       __builtin_amdgcn_s_setprio(0);
;       if (more) lstore(lds + ((it + 1) & 1) * ST);
; #pragma unroll
;       for (int ks = 0; ks < 4; ++ks) {
;         const bf16x8 v0 = *(const bf16x8*)(st + v_rd + ks * 32);
;         const bf16x8 v1 = *(const bf16x8*)(st + v_rd + 32 * LROW + ks * 32);
; #pragma unroll
;         for (int qt = 0; qt < QT; ++qt) {
;           o[0][qt] = MFMA(v0, pf[qt][ks], o[0][qt]);
;           o[1][qt] = MFMA(v1, pf[qt][ks], o[1][qt]);
;         }
;       }
;     } else {
;       if (more) lstore(lds + ((it + 1) & 1) * ST);
;     }
;     __syncthreads();
.Lgqa_nr1:
	v_fmamk_f32 v82, v82, 0x3e38aa3b, v138
	v_fmamk_f32 v114, v114, 0x3e38aa3b, v139
	v_fmamk_f32 v83, v83, 0x3e38aa3b, v138
	v_fmamk_f32 v115, v115, 0x3e38aa3b, v139
	v_fmamk_f32 v84, v84, 0x3e38aa3b, v138
	v_fmamk_f32 v116, v116, 0x3e38aa3b, v139
	v_fmamk_f32 v85, v85, 0x3e38aa3b, v138
	v_fmamk_f32 v117, v117, 0x3e38aa3b, v139
	v_fmamk_f32 v86, v86, 0x3e38aa3b, v138
	v_fmamk_f32 v118, v118, 0x3e38aa3b, v139
	v_fmamk_f32 v87, v87, 0x3e38aa3b, v138
	v_fmamk_f32 v119, v119, 0x3e38aa3b, v139
	v_fmamk_f32 v88, v88, 0x3e38aa3b, v138
	v_fmamk_f32 v120, v120, 0x3e38aa3b, v139
	v_fmamk_f32 v89, v89, 0x3e38aa3b, v138
	v_fmamk_f32 v121, v121, 0x3e38aa3b, v139
	v_exp_f32_e32 v82, v82
	v_exp_f32_e32 v114, v114
	v_exp_f32_e32 v83, v83
	v_exp_f32_e32 v115, v115
	v_exp_f32_e32 v84, v84
	v_exp_f32_e32 v116, v116
	v_exp_f32_e32 v85, v85
	v_exp_f32_e32 v117, v117
	v_exp_f32_e32 v86, v86
	v_exp_f32_e32 v118, v118
	v_exp_f32_e32 v87, v87
	v_exp_f32_e32 v119, v119
	v_exp_f32_e32 v88, v88
	v_exp_f32_e32 v120, v120
	v_exp_f32_e32 v89, v89
	v_exp_f32_e32 v121, v121
	v_fmamk_f32 v90, v90, 0x3e38aa3b, v138
	v_fmamk_f32 v122, v122, 0x3e38aa3b, v139
	v_fmamk_f32 v91, v91, 0x3e38aa3b, v138
	v_fmamk_f32 v123, v123, 0x3e38aa3b, v139
	v_fmamk_f32 v92, v92, 0x3e38aa3b, v138
	v_fmamk_f32 v124, v124, 0x3e38aa3b, v139
	v_fmamk_f32 v93, v93, 0x3e38aa3b, v138
	v_fmamk_f32 v125, v125, 0x3e38aa3b, v139
	v_fmamk_f32 v94, v94, 0x3e38aa3b, v138
	v_fmamk_f32 v126, v126, 0x3e38aa3b, v139
	v_fmamk_f32 v95, v95, 0x3e38aa3b, v138
	v_fmamk_f32 v127, v127, 0x3e38aa3b, v139
	v_fmamk_f32 v96, v96, 0x3e38aa3b, v138
	v_fmamk_f32 v128, v128, 0x3e38aa3b, v139
	v_fmamk_f32 v97, v97, 0x3e38aa3b, v138
	v_fmamk_f32 v129, v129, 0x3e38aa3b, v139
	v_exp_f32_e32 v90, v90
	v_exp_f32_e32 v122, v122
	v_exp_f32_e32 v91, v91
	v_exp_f32_e32 v123, v123
	v_exp_f32_e32 v92, v92
	v_exp_f32_e32 v124, v124
	v_exp_f32_e32 v93, v93
	v_exp_f32_e32 v125, v125
	v_exp_f32_e32 v94, v94
	v_exp_f32_e32 v126, v126
	v_exp_f32_e32 v95, v95
	v_exp_f32_e32 v127, v127
	v_exp_f32_e32 v96, v96
	v_exp_f32_e32 v128, v128
	v_exp_f32_e32 v97, v97
	v_exp_f32_e32 v129, v129
	v_cvt_pk_bf16_f32 v82, v82, v83
	v_cvt_pk_bf16_f32 v114, v114, v115
	v_cvt_pk_bf16_f32 v83, v84, v85
	v_cvt_pk_bf16_f32 v115, v116, v117
	v_cvt_pk_bf16_f32 v84, v86, v87
	v_cvt_pk_bf16_f32 v116, v118, v119
	v_cvt_pk_bf16_f32 v85, v88, v89
	v_cvt_pk_bf16_f32 v117, v120, v121
	v_fmamk_f32 v66, v66, 0x3e38aa3b, v138
	v_fmamk_f32 v98, v98, 0x3e38aa3b, v139
	v_fmamk_f32 v67, v67, 0x3e38aa3b, v138
	v_fmamk_f32 v99, v99, 0x3e38aa3b, v139
	v_fmamk_f32 v68, v68, 0x3e38aa3b, v138
	v_fmamk_f32 v100, v100, 0x3e38aa3b, v139
	v_fmamk_f32 v69, v69, 0x3e38aa3b, v138
	v_fmamk_f32 v101, v101, 0x3e38aa3b, v139
	v_fmamk_f32 v70, v70, 0x3e38aa3b, v138
	v_fmamk_f32 v102, v102, 0x3e38aa3b, v139
	v_fmamk_f32 v71, v71, 0x3e38aa3b, v138
	v_fmamk_f32 v103, v103, 0x3e38aa3b, v139
	v_fmamk_f32 v72, v72, 0x3e38aa3b, v138
	v_fmamk_f32 v104, v104, 0x3e38aa3b, v139
	v_fmamk_f32 v73, v73, 0x3e38aa3b, v138
	v_fmamk_f32 v105, v105, 0x3e38aa3b, v139
	v_exp_f32_e32 v66, v66
	v_exp_f32_e32 v98, v98
	v_exp_f32_e32 v67, v67
	v_exp_f32_e32 v99, v99
	v_exp_f32_e32 v68, v68
	v_exp_f32_e32 v100, v100
	v_exp_f32_e32 v69, v69
	v_exp_f32_e32 v101, v101
	v_exp_f32_e32 v70, v70
	v_exp_f32_e32 v102, v102
	v_exp_f32_e32 v71, v71
	v_exp_f32_e32 v103, v103
	v_exp_f32_e32 v72, v72
	v_exp_f32_e32 v104, v104
	v_exp_f32_e32 v73, v73
	v_exp_f32_e32 v105, v105
	v_cvt_pk_bf16_f32 v90, v90, v91
	v_cvt_pk_bf16_f32 v122, v122, v123
	v_cvt_pk_bf16_f32 v91, v92, v93
	v_cvt_pk_bf16_f32 v123, v124, v125
	v_cvt_pk_bf16_f32 v92, v94, v95
	v_cvt_pk_bf16_f32 v124, v126, v127
	v_cvt_pk_bf16_f32 v93, v96, v97
	v_cvt_pk_bf16_f32 v125, v128, v129
	v_fmamk_f32 v74, v74, 0x3e38aa3b, v138
	v_fmamk_f32 v106, v106, 0x3e38aa3b, v139
	v_fmamk_f32 v75, v75, 0x3e38aa3b, v138
	v_fmamk_f32 v107, v107, 0x3e38aa3b, v139
	v_fmamk_f32 v76, v76, 0x3e38aa3b, v138
	v_fmamk_f32 v108, v108, 0x3e38aa3b, v139
	v_fmamk_f32 v77, v77, 0x3e38aa3b, v138
	v_fmamk_f32 v109, v109, 0x3e38aa3b, v139
	v_fmamk_f32 v78, v78, 0x3e38aa3b, v138
	v_fmamk_f32 v110, v110, 0x3e38aa3b, v139
	v_fmamk_f32 v79, v79, 0x3e38aa3b, v138
	v_fmamk_f32 v111, v111, 0x3e38aa3b, v139
	v_fmamk_f32 v80, v80, 0x3e38aa3b, v138
	v_fmamk_f32 v112, v112, 0x3e38aa3b, v139
	v_fmamk_f32 v81, v81, 0x3e38aa3b, v138
	v_fmamk_f32 v113, v113, 0x3e38aa3b, v139
	v_exp_f32_e32 v74, v74
	v_exp_f32_e32 v106, v106
	v_exp_f32_e32 v75, v75
	v_exp_f32_e32 v107, v107
	v_exp_f32_e32 v76, v76
	v_exp_f32_e32 v108, v108
	v_exp_f32_e32 v77, v77
	v_exp_f32_e32 v109, v109
	v_exp_f32_e32 v78, v78
	v_exp_f32_e32 v110, v110
	v_exp_f32_e32 v79, v79
	v_exp_f32_e32 v111, v111
	v_exp_f32_e32 v80, v80
	v_exp_f32_e32 v112, v112
	v_exp_f32_e32 v81, v81
	v_exp_f32_e32 v113, v113
	v_cvt_pk_bf16_f32 v66, v66, v67
	v_cvt_pk_bf16_f32 v98, v98, v99
	v_cvt_pk_bf16_f32 v67, v68, v69
	v_cvt_pk_bf16_f32 v99, v100, v101
	v_cvt_pk_bf16_f32 v68, v70, v71
	v_cvt_pk_bf16_f32 v100, v102, v103
	v_cvt_pk_bf16_f32 v69, v72, v73
	v_cvt_pk_bf16_f32 v101, v104, v105
	v_cvt_pk_bf16_f32 v74, v74, v75
	v_cvt_pk_bf16_f32 v106, v106, v107
	v_cvt_pk_bf16_f32 v75, v76, v77
	v_cvt_pk_bf16_f32 v107, v108, v109
	v_cvt_pk_bf16_f32 v76, v78, v79
	v_cvt_pk_bf16_f32 v108, v110, v111
	v_cvt_pk_bf16_f32 v77, v80, v81
	v_cvt_pk_bf16_f32 v109, v112, v113
	s_setprio 2
	ds_read_b128 v[86:89], v183 offset:9216
	ds_read_b128 v[94:97], v183 offset:13824
	ds_read_b128 v[70:73], v183 offset:9248
	ds_read_b128 v[78:81], v183 offset:13856
	ds_read_b128 v[118:121], v183 offset:9280
	ds_read_b128 v[126:129], v183 offset:13888
	ds_read_b128 v[102:105], v183 offset:9312
	ds_read_b128 v[110:113], v183 offset:13920
	s_waitcnt lgkmcnt(7)
	v_mfma_f32_32x32x16_bf16 v[50:65], v[86:89], v[82:85], v[50:65]
	v_mfma_f32_32x32x16_bf16 v[18:33], v[86:89], v[114:117], v[18:33]
	s_waitcnt lgkmcnt(6)
	v_mfma_f32_32x32x16_bf16 v[34:49], v[94:97], v[82:85], v[34:49]
	v_mfma_f32_32x32x16_bf16 v[2:17], v[94:97], v[114:117], v[2:17]
	s_waitcnt lgkmcnt(5)
	v_mfma_f32_32x32x16_bf16 v[50:65], v[70:73], v[90:93], v[50:65]
	v_mfma_f32_32x32x16_bf16 v[18:33], v[70:73], v[122:125], v[18:33]
	s_waitcnt lgkmcnt(4)
	v_mfma_f32_32x32x16_bf16 v[34:49], v[78:81], v[90:93], v[34:49]
	v_mfma_f32_32x32x16_bf16 v[2:17], v[78:81], v[122:125], v[2:17]
	s_waitcnt lgkmcnt(3)
	v_mfma_f32_32x32x16_bf16 v[50:65], v[118:121], v[66:69], v[50:65]
	v_mfma_f32_32x32x16_bf16 v[18:33], v[118:121], v[98:101], v[18:33]
	s_waitcnt lgkmcnt(2)
	v_mfma_f32_32x32x16_bf16 v[34:49], v[126:129], v[66:69], v[34:49]
	v_mfma_f32_32x32x16_bf16 v[2:17], v[126:129], v[98:101], v[2:17]
	s_nop 0
	s_add_i32 s1, s1, 1
	s_add_i32 s6, s6, 64
	s_waitcnt vmcnt(0) lgkmcnt(0)
	s_barrier
; #define MFMA(a, b, c) __builtin_amdgcn_mfma_f32_32x32x16_bf16((a), (b), (c), 0, 0, 0)
; template <int DQK, bool BAND, int QT> ...
;     ...
; #pragma unroll
;         for (int qt = 0; qt < QT; ++qt) {
;           o[0][qt] = MFMA(v0, pf[qt][ks], o[0][qt]);
;           o[1][qt] = MFMA(v1, pf[qt][ks], o[1][qt]);
;         }
;       }
;     } else {
;       if (more) lstore(lds + ((it + 1) & 1) * ST);
;     }
;     __syncthreads();
	v_mfma_f32_32x32x16_bf16 v[50:65], v[102:105], v[74:77], v[50:65]
	v_mfma_f32_32x32x16_bf16 v[18:33], v[102:105], v[106:109], v[18:33]
	v_mfma_f32_32x32x16_bf16 v[34:49], v[110:113], v[74:77], v[34:49]
	v_mfma_f32_32x32x16_bf16 v[2:17], v[110:113], v[106:109], v[2:17]
	v_mfma_f32_16x16x32_bf16 v[240:243], v[244:247], v[82:85], v[240:243]
	v_mfma_f32_16x16x32_bf16 v[236:239], v[244:247], v[114:117], v[236:239]
	v_mfma_f32_16x16x32_bf16 v[240:243], v[244:247], v[90:93], v[240:243]
	v_mfma_f32_16x16x32_bf16 v[236:239], v[244:247], v[122:125], v[236:239]
	v_mfma_f32_16x16x32_bf16 v[240:243], v[244:247], v[66:69], v[240:243]
	v_mfma_f32_16x16x32_bf16 v[236:239], v[244:247], v[98:101], v[236:239]
	v_mfma_f32_16x16x32_bf16 v[240:243], v[244:247], v[74:77], v[240:243]
	v_mfma_f32_16x16x32_bf16 v[236:239], v[244:247], v[106:109], v[236:239]
	s_cmp_lg_u32 s21, s1
	s_cbranch_scc0 .Lgqa_u2exit
	s_nop 0

; #define MFMA(a, b, c) __builtin_amdgcn_mfma_f32_32x32x16_bf16((a), (b), (c), 0, 0, 0)
; DI unsigned pk2(float a, float b) { f32x2 v = {a, b}; bf16x2_t r = __builtin_convertvector(v, bf16x2_t); return __builtin_bit_cast(unsigned, r); }
; template <int DQK, bool BAND, int QT> ...
;     ...
;         const float mc = -m[qt] * cc;
;         float ls = 0.f;
; #pragma unroll
;         for (int a = 0; a < 2; ++a) {
; #pragma unroll
;           for (int r = 0; r < 16; ++r) { const float pv = __builtin_amdgcn_exp2f(fmaf(s[a][qt][r], cc, mc)); s[a][qt][r] = pv; ls += pv; }
; #pragma unroll
;           for (int s2 = 0; s2 < 2; ++s2) {
;             u32x4 pk;
;             pk.x = pk2(s[a][qt][8 * s2 + 0], s[a][qt][8 * s2 + 1]);
;             pk.y = pk2(s[a][qt][8 * s2 + 2], s[a][qt][8 * s2 + 3]);
;             pk.z = pk2(s[a][qt][8 * s2 + 4], s[a][qt][8 * s2 + 5]);
;             pk.w = pk2(s[a][qt][8 * s2 + 6], s[a][qt][8 * s2 + 7]);
;             pf[qt][a * 2 + s2] = __builtin_bit_cast(bf16x8, pk);
;           }
;         }
;         l[qt] += ls;
;       }
;       __builtin_amdgcn_s_setprio(0);
;       if (more) lstore(lds + ((it + 1) & 1) * ST);
; #pragma unroll
;       for (int ks = 0; ks < 4; ++ks) {
;         const bf16x8 v0 = *(const bf16x8*)(st + v_rd + ks * 32);
;         const bf16x8 v1 = *(const bf16x8*)(st + v_rd + 32 * LROW + ks * 32);
; #pragma unroll
;         for (int qt = 0; qt < QT; ++qt) {
;           o[0][qt] = MFMA(v0, pf[qt][ks], o[0][qt]);
;           o[1][qt] = MFMA(v1, pf[qt][ks], o[1][qt]);
;         }
;       }
;     } else {
;       if (more) lstore(lds + ((it + 1) & 1) * ST);
;     }
;     __syncthreads();
.Lgqab_nr1:
	v_fmamk_f32 v82, v82, 0x3e38aa3b, v138
	v_fmamk_f32 v114, v114, 0x3e38aa3b, v139
	v_fmamk_f32 v83, v83, 0x3e38aa3b, v138
	v_fmamk_f32 v115, v115, 0x3e38aa3b, v139
	v_fmamk_f32 v84, v84, 0x3e38aa3b, v138
	v_fmamk_f32 v116, v116, 0x3e38aa3b, v139
	v_fmamk_f32 v85, v85, 0x3e38aa3b, v138
	v_fmamk_f32 v117, v117, 0x3e38aa3b, v139
	v_fmamk_f32 v86, v86, 0x3e38aa3b, v138
	v_fmamk_f32 v118, v118, 0x3e38aa3b, v139
	v_fmamk_f32 v87, v87, 0x3e38aa3b, v138
	v_fmamk_f32 v119, v119, 0x3e38aa3b, v139
	v_fmamk_f32 v88, v88, 0x3e38aa3b, v138
	v_fmamk_f32 v120, v120, 0x3e38aa3b, v139
	v_fmamk_f32 v89, v89, 0x3e38aa3b, v138
	v_fmamk_f32 v121, v121, 0x3e38aa3b, v139
	v_exp_f32_e32 v82, v82
	v_exp_f32_e32 v114, v114
	v_exp_f32_e32 v83, v83
	v_exp_f32_e32 v115, v115
	v_exp_f32_e32 v84, v84
	v_exp_f32_e32 v116, v116
	v_exp_f32_e32 v85, v85
	v_exp_f32_e32 v117, v117
	v_exp_f32_e32 v86, v86
	v_exp_f32_e32 v118, v118
	v_exp_f32_e32 v87, v87
	v_exp_f32_e32 v119, v119
	v_exp_f32_e32 v88, v88
	v_exp_f32_e32 v120, v120
	v_exp_f32_e32 v89, v89
	v_exp_f32_e32 v121, v121
	v_fmamk_f32 v90, v90, 0x3e38aa3b, v138
	v_fmamk_f32 v122, v122, 0x3e38aa3b, v139
	v_fmamk_f32 v91, v91, 0x3e38aa3b, v138
	v_fmamk_f32 v123, v123, 0x3e38aa3b, v139
	v_fmamk_f32 v92, v92, 0x3e38aa3b, v138
	v_fmamk_f32 v124, v124, 0x3e38aa3b, v139
	v_fmamk_f32 v93, v93, 0x3e38aa3b, v138
	v_fmamk_f32 v125, v125, 0x3e38aa3b, v139
	v_fmamk_f32 v94, v94, 0x3e38aa3b, v138
	v_fmamk_f32 v126, v126, 0x3e38aa3b, v139
	v_fmamk_f32 v95, v95, 0x3e38aa3b, v138
	v_fmamk_f32 v127, v127, 0x3e38aa3b, v139
	v_fmamk_f32 v96, v96, 0x3e38aa3b, v138
	v_fmamk_f32 v128, v128, 0x3e38aa3b, v139
	v_fmamk_f32 v97, v97, 0x3e38aa3b, v138
	v_fmamk_f32 v129, v129, 0x3e38aa3b, v139
	v_exp_f32_e32 v90, v90
	v_exp_f32_e32 v122, v122
	v_exp_f32_e32 v91, v91
	v_exp_f32_e32 v123, v123
	v_exp_f32_e32 v92, v92
	v_exp_f32_e32 v124, v124
	v_exp_f32_e32 v93, v93
	v_exp_f32_e32 v125, v125
	v_exp_f32_e32 v94, v94
	v_exp_f32_e32 v126, v126
	v_exp_f32_e32 v95, v95
	v_exp_f32_e32 v127, v127
	v_exp_f32_e32 v96, v96
	v_exp_f32_e32 v128, v128
	v_exp_f32_e32 v97, v97
	v_exp_f32_e32 v129, v129
	v_cvt_pk_bf16_f32 v82, v82, v83
	v_cvt_pk_bf16_f32 v114, v114, v115
	v_cvt_pk_bf16_f32 v83, v84, v85
	v_cvt_pk_bf16_f32 v115, v116, v117
	v_cvt_pk_bf16_f32 v84, v86, v87
	v_cvt_pk_bf16_f32 v116, v118, v119
	v_cvt_pk_bf16_f32 v85, v88, v89
	v_cvt_pk_bf16_f32 v117, v120, v121
	v_fmamk_f32 v66, v66, 0x3e38aa3b, v138
	v_fmamk_f32 v98, v98, 0x3e38aa3b, v139
	v_fmamk_f32 v67, v67, 0x3e38aa3b, v138
	v_fmamk_f32 v99, v99, 0x3e38aa3b, v139
	v_fmamk_f32 v68, v68, 0x3e38aa3b, v138
	v_fmamk_f32 v100, v100, 0x3e38aa3b, v139
	v_fmamk_f32 v69, v69, 0x3e38aa3b, v138
	v_fmamk_f32 v101, v101, 0x3e38aa3b, v139
	v_fmamk_f32 v70, v70, 0x3e38aa3b, v138
	v_fmamk_f32 v102, v102, 0x3e38aa3b, v139
	v_fmamk_f32 v71, v71, 0x3e38aa3b, v138
	v_fmamk_f32 v103, v103, 0x3e38aa3b, v139
	v_fmamk_f32 v72, v72, 0x3e38aa3b, v138
	v_fmamk_f32 v104, v104, 0x3e38aa3b, v139
	v_fmamk_f32 v73, v73, 0x3e38aa3b, v138
	v_fmamk_f32 v105, v105, 0x3e38aa3b, v139
	v_exp_f32_e32 v66, v66
	v_exp_f32_e32 v98, v98
	v_exp_f32_e32 v67, v67
	v_exp_f32_e32 v99, v99
	v_exp_f32_e32 v68, v68
	v_exp_f32_e32 v100, v100
	v_exp_f32_e32 v69, v69
	v_exp_f32_e32 v101, v101
	v_exp_f32_e32 v70, v70
	v_exp_f32_e32 v102, v102
	v_exp_f32_e32 v71, v71
	v_exp_f32_e32 v103, v103
	v_exp_f32_e32 v72, v72
	v_exp_f32_e32 v104, v104
	v_exp_f32_e32 v73, v73
	v_exp_f32_e32 v105, v105
	v_cvt_pk_bf16_f32 v90, v90, v91
	v_cvt_pk_bf16_f32 v122, v122, v123
	v_cvt_pk_bf16_f32 v91, v92, v93
	v_cvt_pk_bf16_f32 v123, v124, v125
	v_cvt_pk_bf16_f32 v92, v94, v95
	v_cvt_pk_bf16_f32 v124, v126, v127
	v_cvt_pk_bf16_f32 v93, v96, v97
	v_cvt_pk_bf16_f32 v125, v128, v129
	v_fmamk_f32 v74, v74, 0x3e38aa3b, v138
	v_fmamk_f32 v106, v106, 0x3e38aa3b, v139
	v_fmamk_f32 v75, v75, 0x3e38aa3b, v138
	v_fmamk_f32 v107, v107, 0x3e38aa3b, v139
	v_fmamk_f32 v76, v76, 0x3e38aa3b, v138
	v_fmamk_f32 v108, v108, 0x3e38aa3b, v139
	v_fmamk_f32 v77, v77, 0x3e38aa3b, v138
	v_fmamk_f32 v109, v109, 0x3e38aa3b, v139
	v_fmamk_f32 v78, v78, 0x3e38aa3b, v138
	v_fmamk_f32 v110, v110, 0x3e38aa3b, v139
	v_fmamk_f32 v79, v79, 0x3e38aa3b, v138
	v_fmamk_f32 v111, v111, 0x3e38aa3b, v139
	v_fmamk_f32 v80, v80, 0x3e38aa3b, v138
	v_fmamk_f32 v112, v112, 0x3e38aa3b, v139
	v_fmamk_f32 v81, v81, 0x3e38aa3b, v138
	v_fmamk_f32 v113, v113, 0x3e38aa3b, v139
	v_exp_f32_e32 v74, v74
	v_exp_f32_e32 v106, v106
	v_exp_f32_e32 v75, v75
	v_exp_f32_e32 v107, v107
	v_exp_f32_e32 v76, v76
	v_exp_f32_e32 v108, v108
	v_exp_f32_e32 v77, v77
	v_exp_f32_e32 v109, v109
	v_exp_f32_e32 v78, v78
	v_exp_f32_e32 v110, v110
	v_exp_f32_e32 v79, v79
	v_exp_f32_e32 v111, v111
	v_exp_f32_e32 v80, v80
	v_exp_f32_e32 v112, v112
	v_exp_f32_e32 v81, v81
	v_exp_f32_e32 v113, v113
	v_cvt_pk_bf16_f32 v66, v66, v67
	v_cvt_pk_bf16_f32 v98, v98, v99
	v_cvt_pk_bf16_f32 v67, v68, v69
	v_cvt_pk_bf16_f32 v99, v100, v101
	v_cvt_pk_bf16_f32 v68, v70, v71
	v_cvt_pk_bf16_f32 v100, v102, v103
	v_cvt_pk_bf16_f32 v69, v72, v73
	v_cvt_pk_bf16_f32 v101, v104, v105
	v_cvt_pk_bf16_f32 v74, v74, v75
	v_cvt_pk_bf16_f32 v106, v106, v107
	v_cvt_pk_bf16_f32 v75, v76, v77
	v_cvt_pk_bf16_f32 v107, v108, v109
	v_cvt_pk_bf16_f32 v76, v78, v79
	v_cvt_pk_bf16_f32 v108, v110, v111
	v_cvt_pk_bf16_f32 v77, v80, v81
	v_cvt_pk_bf16_f32 v109, v112, v113
	s_setprio 2
	ds_read_b128 v[86:89], v141 offset:9216
	ds_read_b128 v[94:97], v141 offset:13824
	ds_read_b128 v[70:73], v141 offset:9248
	ds_read_b128 v[78:81], v141 offset:13856
	ds_read_b128 v[118:121], v141 offset:9280
	ds_read_b128 v[126:129], v141 offset:13888
	ds_read_b128 v[102:105], v141 offset:9312
	ds_read_b128 v[110:113], v141 offset:13920
	s_waitcnt lgkmcnt(7)
	v_mfma_f32_32x32x16_bf16 v[50:65], v[86:89], v[82:85], v[50:65]
	v_mfma_f32_32x32x16_bf16 v[18:33], v[86:89], v[114:117], v[18:33]
	s_waitcnt lgkmcnt(6)
	v_mfma_f32_32x32x16_bf16 v[34:49], v[94:97], v[82:85], v[34:49]
	v_mfma_f32_32x32x16_bf16 v[2:17], v[94:97], v[114:117], v[2:17]
	s_waitcnt lgkmcnt(5)
	v_mfma_f32_32x32x16_bf16 v[50:65], v[70:73], v[90:93], v[50:65]
	v_mfma_f32_32x32x16_bf16 v[18:33], v[70:73], v[122:125], v[18:33]
	s_waitcnt lgkmcnt(4)
	v_mfma_f32_32x32x16_bf16 v[34:49], v[78:81], v[90:93], v[34:49]
	v_mfma_f32_32x32x16_bf16 v[2:17], v[78:81], v[122:125], v[2:17]
	s_waitcnt lgkmcnt(3)
	v_mfma_f32_32x32x16_bf16 v[50:65], v[118:121], v[66:69], v[50:65]
	v_mfma_f32_32x32x16_bf16 v[18:33], v[118:121], v[98:101], v[18:33]
	s_waitcnt lgkmcnt(2)
	v_mfma_f32_32x32x16_bf16 v[34:49], v[126:129], v[66:69], v[34:49]
	v_mfma_f32_32x32x16_bf16 v[2:17], v[126:129], v[98:101], v[2:17]
	s_nop 0
	s_add_i32 s1, s1, 1
	s_add_i32 s6, s6, 64
	s_waitcnt vmcnt(0) lgkmcnt(0)
	s_barrier
; #define MFMA(a, b, c) __builtin_amdgcn_mfma_f32_32x32x16_bf16((a), (b), (c), 0, 0, 0)
; template <int DQK, bool BAND, int QT> ...
;     ...
; #pragma unroll
;         for (int qt = 0; qt < QT; ++qt) {
;           o[0][qt] = MFMA(v0, pf[qt][ks], o[0][qt]);
;           o[1][qt] = MFMA(v1, pf[qt][ks], o[1][qt]);
;         }
;       }
;     } else {
;       if (more) lstore(lds + ((it + 1) & 1) * ST);
;     }
;     __syncthreads();
	v_mfma_f32_32x32x16_bf16 v[50:65], v[102:105], v[74:77], v[50:65]
	v_mfma_f32_32x32x16_bf16 v[18:33], v[102:105], v[106:109], v[18:33]
	v_mfma_f32_32x32x16_bf16 v[34:49], v[110:113], v[74:77], v[34:49]
	v_mfma_f32_32x32x16_bf16 v[2:17], v[110:113], v[106:109], v[2:17]
	v_mfma_f32_16x16x32_bf16 v[240:243], v[244:247], v[82:85], v[240:243]
	v_mfma_f32_16x16x32_bf16 v[236:239], v[244:247], v[114:117], v[236:239]
	v_mfma_f32_16x16x32_bf16 v[240:243], v[244:247], v[90:93], v[240:243]
	v_mfma_f32_16x16x32_bf16 v[236:239], v[244:247], v[122:125], v[236:239]
	v_mfma_f32_16x16x32_bf16 v[240:243], v[244:247], v[66:69], v[240:243]
	v_mfma_f32_16x16x32_bf16 v[236:239], v[244:247], v[98:101], v[236:239]
	v_mfma_f32_16x16x32_bf16 v[240:243], v[244:247], v[74:77], v[240:243]
	v_mfma_f32_16x16x32_bf16 v[236:239], v[244:247], v[106:109], v[236:239]
	s_cmp_lg_u32 s21, s1
	s_cbranch_scc1 .Lgqa_top

; #define MFMA(a, b, c) __builtin_amdgcn_mfma_f32_32x32x16_bf16((a), (b), (c), 0, 0, 0)
; DI unsigned pk2(float a, float b) { f32x2 v = {a, b}; bf16x2_t r = __builtin_convertvector(v, bf16x2_t); return __builtin_bit_cast(unsigned, r); }
; template <int DQK, bool BAND, int QT> ...
;     ...
;         const float mc = -m[qt] * cc;
;         float ls = 0.f;
; #pragma unroll
;         for (int a = 0; a < 2; ++a) {
; #pragma unroll
;           for (int r = 0; r < 16; ++r) { const float pv = __builtin_amdgcn_exp2f(fmaf(s[a][qt][r], cc, mc)); s[a][qt][r] = pv; ls += pv; }
; #pragma unroll
;           for (int s2 = 0; s2 < 2; ++s2) {
;             u32x4 pk;
;             pk.x = pk2(s[a][qt][8 * s2 + 0], s[a][qt][8 * s2 + 1]);
;             pk.y = pk2(s[a][qt][8 * s2 + 2], s[a][qt][8 * s2 + 3]);
;             pk.z = pk2(s[a][qt][8 * s2 + 4], s[a][qt][8 * s2 + 5]);
;             pk.w = pk2(s[a][qt][8 * s2 + 6], s[a][qt][8 * s2 + 7]);
;             pf[qt][a * 2 + s2] = __builtin_bit_cast(bf16x8, pk);
;           }
;         }
;         l[qt] += ls;
;       }
;       __builtin_amdgcn_s_setprio(0);
;       if (more) lstore(lds + ((it + 1) & 1) * ST);
; #pragma unroll
;       for (int ks = 0; ks < 4; ++ks) {
;         const bf16x8 v0 = *(const bf16x8*)(st + v_rd + ks * 32);
;         const bf16x8 v1 = *(const bf16x8*)(st + v_rd + 32 * LROW + ks * 32);
; #pragma unroll
;         for (int qt = 0; qt < QT; ++qt) {
;           o[0][qt] = MFMA(v0, pf[qt][ks], o[0][qt]);
;           o[1][qt] = MFMA(v1, pf[qt][ks], o[1][qt]);
;         }
;       }
;     } else {
;       if (more) lstore(lds + ((it + 1) & 1) * ST);
;     }
;     __syncthreads();
.Lmla_nr1:
	v_fmamk_f32 v82, v82, 0x3e16c740, v210
	v_fmamk_f32 v114, v114, 0x3e16c740, v211
	v_fmamk_f32 v83, v83, 0x3e16c740, v210
	v_fmamk_f32 v115, v115, 0x3e16c740, v211
	v_fmamk_f32 v84, v84, 0x3e16c740, v210
	v_fmamk_f32 v116, v116, 0x3e16c740, v211
	v_fmamk_f32 v85, v85, 0x3e16c740, v210
	v_fmamk_f32 v117, v117, 0x3e16c740, v211
	v_fmamk_f32 v86, v86, 0x3e16c740, v210
	v_fmamk_f32 v118, v118, 0x3e16c740, v211
	v_fmamk_f32 v87, v87, 0x3e16c740, v210
	v_fmamk_f32 v119, v119, 0x3e16c740, v211
	v_fmamk_f32 v88, v88, 0x3e16c740, v210
	v_fmamk_f32 v120, v120, 0x3e16c740, v211
	v_fmamk_f32 v89, v89, 0x3e16c740, v210
	v_fmamk_f32 v121, v121, 0x3e16c740, v211
	v_exp_f32_e32 v82, v82
	v_exp_f32_e32 v114, v114
	v_exp_f32_e32 v83, v83
	v_exp_f32_e32 v115, v115
	v_exp_f32_e32 v84, v84
	v_exp_f32_e32 v116, v116
	v_exp_f32_e32 v85, v85
	v_exp_f32_e32 v117, v117
	v_exp_f32_e32 v86, v86
	v_exp_f32_e32 v118, v118
	v_exp_f32_e32 v87, v87
	v_exp_f32_e32 v119, v119
	v_exp_f32_e32 v88, v88
	v_exp_f32_e32 v120, v120
	v_exp_f32_e32 v89, v89
	v_exp_f32_e32 v121, v121
	v_fmamk_f32 v90, v90, 0x3e16c740, v210
	v_fmamk_f32 v122, v122, 0x3e16c740, v211
	v_fmamk_f32 v91, v91, 0x3e16c740, v210
	v_fmamk_f32 v123, v123, 0x3e16c740, v211
	v_fmamk_f32 v92, v92, 0x3e16c740, v210
	v_fmamk_f32 v124, v124, 0x3e16c740, v211
	v_fmamk_f32 v93, v93, 0x3e16c740, v210
	v_fmamk_f32 v125, v125, 0x3e16c740, v211
	v_fmamk_f32 v94, v94, 0x3e16c740, v210
	v_fmamk_f32 v126, v126, 0x3e16c740, v211
	v_fmamk_f32 v95, v95, 0x3e16c740, v210
	v_fmamk_f32 v127, v127, 0x3e16c740, v211
	v_fmamk_f32 v96, v96, 0x3e16c740, v210
	v_fmamk_f32 v128, v128, 0x3e16c740, v211
	v_fmamk_f32 v97, v97, 0x3e16c740, v210
	v_fmamk_f32 v129, v129, 0x3e16c740, v211
	v_exp_f32_e32 v90, v90
	v_exp_f32_e32 v122, v122
	v_exp_f32_e32 v91, v91
	v_exp_f32_e32 v123, v123
	v_exp_f32_e32 v92, v92
	v_exp_f32_e32 v124, v124
	v_exp_f32_e32 v93, v93
	v_exp_f32_e32 v125, v125
	v_exp_f32_e32 v94, v94
	v_exp_f32_e32 v126, v126
	v_exp_f32_e32 v95, v95
	v_exp_f32_e32 v127, v127
	v_exp_f32_e32 v96, v96
	v_exp_f32_e32 v128, v128
	v_exp_f32_e32 v97, v97
	v_exp_f32_e32 v129, v129
	v_cvt_pk_bf16_f32 v82, v82, v83
	v_cvt_pk_bf16_f32 v114, v114, v115
	v_cvt_pk_bf16_f32 v83, v84, v85
	v_cvt_pk_bf16_f32 v115, v116, v117
	v_cvt_pk_bf16_f32 v84, v86, v87
	v_cvt_pk_bf16_f32 v116, v118, v119
	v_cvt_pk_bf16_f32 v85, v88, v89
	v_cvt_pk_bf16_f32 v117, v120, v121
	v_fmamk_f32 v66, v66, 0x3e16c740, v210
	v_fmamk_f32 v98, v98, 0x3e16c740, v211
	v_fmamk_f32 v67, v67, 0x3e16c740, v210
	v_fmamk_f32 v99, v99, 0x3e16c740, v211
	v_fmamk_f32 v68, v68, 0x3e16c740, v210
	v_fmamk_f32 v100, v100, 0x3e16c740, v211
	v_fmamk_f32 v69, v69, 0x3e16c740, v210
	v_fmamk_f32 v101, v101, 0x3e16c740, v211
	v_fmamk_f32 v70, v70, 0x3e16c740, v210
	v_fmamk_f32 v102, v102, 0x3e16c740, v211
	v_fmamk_f32 v71, v71, 0x3e16c740, v210
	v_fmamk_f32 v103, v103, 0x3e16c740, v211
	v_fmamk_f32 v72, v72, 0x3e16c740, v210
	v_fmamk_f32 v104, v104, 0x3e16c740, v211
	v_fmamk_f32 v73, v73, 0x3e16c740, v210
	v_fmamk_f32 v105, v105, 0x3e16c740, v211
	v_exp_f32_e32 v66, v66
	v_exp_f32_e32 v98, v98
	v_exp_f32_e32 v67, v67
	v_exp_f32_e32 v99, v99
	v_exp_f32_e32 v68, v68
	v_exp_f32_e32 v100, v100
	v_exp_f32_e32 v69, v69
	v_exp_f32_e32 v101, v101
	v_exp_f32_e32 v70, v70
	v_exp_f32_e32 v102, v102
	v_exp_f32_e32 v71, v71
	v_exp_f32_e32 v103, v103
	v_exp_f32_e32 v72, v72
	v_exp_f32_e32 v104, v104
	v_exp_f32_e32 v73, v73
	v_exp_f32_e32 v105, v105
	v_cvt_pk_bf16_f32 v90, v90, v91
	v_cvt_pk_bf16_f32 v122, v122, v123
	v_cvt_pk_bf16_f32 v91, v92, v93
	v_cvt_pk_bf16_f32 v123, v124, v125
	v_cvt_pk_bf16_f32 v92, v94, v95
	v_cvt_pk_bf16_f32 v124, v126, v127
	v_cvt_pk_bf16_f32 v93, v96, v97
	v_cvt_pk_bf16_f32 v125, v128, v129
	v_fmamk_f32 v74, v74, 0x3e16c740, v210
	v_fmamk_f32 v106, v106, 0x3e16c740, v211
	v_fmamk_f32 v75, v75, 0x3e16c740, v210
	v_fmamk_f32 v107, v107, 0x3e16c740, v211
	v_fmamk_f32 v76, v76, 0x3e16c740, v210
	v_fmamk_f32 v108, v108, 0x3e16c740, v211
	v_fmamk_f32 v77, v77, 0x3e16c740, v210
	v_fmamk_f32 v109, v109, 0x3e16c740, v211
	v_fmamk_f32 v78, v78, 0x3e16c740, v210
	v_fmamk_f32 v110, v110, 0x3e16c740, v211
	v_fmamk_f32 v79, v79, 0x3e16c740, v210
	v_fmamk_f32 v111, v111, 0x3e16c740, v211
	v_fmamk_f32 v80, v80, 0x3e16c740, v210
	v_fmamk_f32 v112, v112, 0x3e16c740, v211
	v_fmamk_f32 v81, v81, 0x3e16c740, v210
	v_fmamk_f32 v113, v113, 0x3e16c740, v211
	v_exp_f32_e32 v74, v74
	v_exp_f32_e32 v106, v106
	v_exp_f32_e32 v75, v75
	v_exp_f32_e32 v107, v107
	v_exp_f32_e32 v76, v76
	v_exp_f32_e32 v108, v108
	v_exp_f32_e32 v77, v77
	v_exp_f32_e32 v109, v109
	v_exp_f32_e32 v78, v78
	v_exp_f32_e32 v110, v110
	v_exp_f32_e32 v79, v79
	v_exp_f32_e32 v111, v111
	v_exp_f32_e32 v80, v80
	v_exp_f32_e32 v112, v112
	v_exp_f32_e32 v81, v81
	v_exp_f32_e32 v113, v113
	v_cvt_pk_bf16_f32 v66, v66, v67
	v_cvt_pk_bf16_f32 v98, v98, v99
	v_cvt_pk_bf16_f32 v67, v68, v69
	v_cvt_pk_bf16_f32 v99, v100, v101
	v_cvt_pk_bf16_f32 v68, v70, v71
	v_cvt_pk_bf16_f32 v100, v102, v103
	v_cvt_pk_bf16_f32 v69, v72, v73
	v_cvt_pk_bf16_f32 v101, v104, v105
	v_cvt_pk_bf16_f32 v74, v74, v75
	v_cvt_pk_bf16_f32 v106, v106, v107
	v_cvt_pk_bf16_f32 v75, v76, v77
	v_cvt_pk_bf16_f32 v107, v108, v109
	v_cvt_pk_bf16_f32 v76, v78, v79
	v_cvt_pk_bf16_f32 v108, v110, v111
	v_cvt_pk_bf16_f32 v77, v80, v81
	v_cvt_pk_bf16_f32 v109, v112, v113
	s_setprio 2
	ds_read_b128 v[86:89], v234 offset:13312
	ds_read_b128 v[94:97], v234 offset:17920
	ds_read_b128 v[70:73], v234 offset:13344
	ds_read_b128 v[78:81], v234 offset:17952
	ds_read_b128 v[118:121], v234 offset:13376
	ds_read_b128 v[126:129], v234 offset:17984
	ds_read_b128 v[102:105], v234 offset:13408
	ds_read_b128 v[110:113], v234 offset:18016
	s_waitcnt lgkmcnt(7)
	v_mfma_f32_32x32x16_bf16 v[50:65], v[86:89], v[82:85], v[50:65]
	v_mfma_f32_32x32x16_bf16 v[18:33], v[86:89], v[114:117], v[18:33]
	s_waitcnt lgkmcnt(6)
	v_mfma_f32_32x32x16_bf16 v[34:49], v[94:97], v[82:85], v[34:49]
	v_mfma_f32_32x32x16_bf16 v[2:17], v[94:97], v[114:117], v[2:17]
	s_waitcnt lgkmcnt(5)
	v_mfma_f32_32x32x16_bf16 v[50:65], v[70:73], v[90:93], v[50:65]
	v_mfma_f32_32x32x16_bf16 v[18:33], v[70:73], v[122:125], v[18:33]
	s_waitcnt lgkmcnt(4)
	v_mfma_f32_32x32x16_bf16 v[34:49], v[78:81], v[90:93], v[34:49]
	v_mfma_f32_32x32x16_bf16 v[2:17], v[78:81], v[122:125], v[2:17]
	s_waitcnt lgkmcnt(3)
	v_mfma_f32_32x32x16_bf16 v[50:65], v[118:121], v[66:69], v[50:65]
	v_mfma_f32_32x32x16_bf16 v[18:33], v[118:121], v[98:101], v[18:33]
	s_waitcnt lgkmcnt(2)
	v_mfma_f32_32x32x16_bf16 v[34:49], v[126:129], v[66:69], v[34:49]
	v_mfma_f32_32x32x16_bf16 v[2:17], v[126:129], v[98:101], v[2:17]
	s_nop 0
	s_add_i32 s1, s1, 1
	s_add_i32 s6, s6, 64
	s_waitcnt vmcnt(0) lgkmcnt(0)
	s_barrier
; #define MFMA(a, b, c) __builtin_amdgcn_mfma_f32_32x32x16_bf16((a), (b), (c), 0, 0, 0)
; template <int DQK, bool BAND, int QT> ...
;     ...
; #pragma unroll
;         for (int qt = 0; qt < QT; ++qt) {
;           o[0][qt] = MFMA(v0, pf[qt][ks], o[0][qt]);
;           o[1][qt] = MFMA(v1, pf[qt][ks], o[1][qt]);
;         }
;       }
;     } else {
;       if (more) lstore(lds + ((it + 1) & 1) * ST);
;     }
;     __syncthreads();
	v_mfma_f32_32x32x16_bf16 v[50:65], v[102:105], v[74:77], v[50:65]
	v_mfma_f32_32x32x16_bf16 v[18:33], v[102:105], v[106:109], v[18:33]
	v_mfma_f32_32x32x16_bf16 v[34:49], v[110:113], v[74:77], v[34:49]
	v_mfma_f32_32x32x16_bf16 v[2:17], v[110:113], v[106:109], v[2:17]
	v_mfma_f32_16x16x32_bf16 v[134:137], v[130:133], v[82:85], v[134:137]
	v_mfma_f32_16x16x32_bf16 v[138:141], v[130:133], v[114:117], v[138:141]
	v_mfma_f32_16x16x32_bf16 v[134:137], v[130:133], v[90:93], v[134:137]
	v_mfma_f32_16x16x32_bf16 v[138:141], v[130:133], v[122:125], v[138:141]
	v_mfma_f32_16x16x32_bf16 v[134:137], v[130:133], v[66:69], v[134:137]
	v_mfma_f32_16x16x32_bf16 v[138:141], v[130:133], v[98:101], v[138:141]
	v_mfma_f32_16x16x32_bf16 v[134:137], v[130:133], v[74:77], v[134:137]
	v_mfma_f32_16x16x32_bf16 v[138:141], v[130:133], v[106:109], v[138:141]
	s_cmp_lg_u32 s21, s1
	s_cbranch_scc0 .Lmla_u2exit

; #define MFMA(a, b, c) __builtin_amdgcn_mfma_f32_32x32x16_bf16((a), (b), (c), 0, 0, 0)
; DI unsigned pk2(float a, float b) { f32x2 v = {a, b}; bf16x2_t r = __builtin_convertvector(v, bf16x2_t); return __builtin_bit_cast(unsigned, r); }
; template <int DQK, bool BAND, int QT> ...
;     ...
;         const float mc = -m[qt] * cc;
;         float ls = 0.f;
; #pragma unroll
;         for (int a = 0; a < 2; ++a) {
; #pragma unroll
;           for (int r = 0; r < 16; ++r) { const float pv = __builtin_amdgcn_exp2f(fmaf(s[a][qt][r], cc, mc)); s[a][qt][r] = pv; ls += pv; }
; #pragma unroll
;           for (int s2 = 0; s2 < 2; ++s2) {
;             u32x4 pk;
;             pk.x = pk2(s[a][qt][8 * s2 + 0], s[a][qt][8 * s2 + 1]);
;             pk.y = pk2(s[a][qt][8 * s2 + 2], s[a][qt][8 * s2 + 3]);
;             pk.z = pk2(s[a][qt][8 * s2 + 4], s[a][qt][8 * s2 + 5]);
;             pk.w = pk2(s[a][qt][8 * s2 + 6], s[a][qt][8 * s2 + 7]);
;             pf[qt][a * 2 + s2] = __builtin_bit_cast(bf16x8, pk);
;           }
;         }
;         l[qt] += ls;
;       }
;       __builtin_amdgcn_s_setprio(0);
;       if (more) lstore(lds + ((it + 1) & 1) * ST);
; #pragma unroll
;       for (int ks = 0; ks < 4; ++ks) {
;         const bf16x8 v0 = *(const bf16x8*)(st + v_rd + ks * 32);
;         const bf16x8 v1 = *(const bf16x8*)(st + v_rd + 32 * LROW + ks * 32);
; #pragma unroll
;         for (int qt = 0; qt < QT; ++qt) {
;           o[0][qt] = MFMA(v0, pf[qt][ks], o[0][qt]);
;           o[1][qt] = MFMA(v1, pf[qt][ks], o[1][qt]);
;         }
;       }
;     } else {
;       if (more) lstore(lds + ((it + 1) & 1) * ST);
;     }
;     __syncthreads();
.Lmlab_nr1:
	v_fmamk_f32 v82, v82, 0x3e16c740, v210
	v_fmamk_f32 v114, v114, 0x3e16c740, v211
	v_fmamk_f32 v83, v83, 0x3e16c740, v210
	v_fmamk_f32 v115, v115, 0x3e16c740, v211
	v_fmamk_f32 v84, v84, 0x3e16c740, v210
	v_fmamk_f32 v116, v116, 0x3e16c740, v211
	v_fmamk_f32 v85, v85, 0x3e16c740, v210
	v_fmamk_f32 v117, v117, 0x3e16c740, v211
	v_fmamk_f32 v86, v86, 0x3e16c740, v210
	v_fmamk_f32 v118, v118, 0x3e16c740, v211
	v_fmamk_f32 v87, v87, 0x3e16c740, v210
	v_fmamk_f32 v119, v119, 0x3e16c740, v211
	v_fmamk_f32 v88, v88, 0x3e16c740, v210
	v_fmamk_f32 v120, v120, 0x3e16c740, v211
	v_fmamk_f32 v89, v89, 0x3e16c740, v210
	v_fmamk_f32 v121, v121, 0x3e16c740, v211
	v_exp_f32_e32 v82, v82
	v_exp_f32_e32 v114, v114
	v_exp_f32_e32 v83, v83
	v_exp_f32_e32 v115, v115
	v_exp_f32_e32 v84, v84
	v_exp_f32_e32 v116, v116
	v_exp_f32_e32 v85, v85
	v_exp_f32_e32 v117, v117
	v_exp_f32_e32 v86, v86
	v_exp_f32_e32 v118, v118
	v_exp_f32_e32 v87, v87
	v_exp_f32_e32 v119, v119
	v_exp_f32_e32 v88, v88
	v_exp_f32_e32 v120, v120
	v_exp_f32_e32 v89, v89
	v_exp_f32_e32 v121, v121
	v_fmamk_f32 v90, v90, 0x3e16c740, v210
	v_fmamk_f32 v122, v122, 0x3e16c740, v211
	v_fmamk_f32 v91, v91, 0x3e16c740, v210
	v_fmamk_f32 v123, v123, 0x3e16c740, v211
	v_fmamk_f32 v92, v92, 0x3e16c740, v210
	v_fmamk_f32 v124, v124, 0x3e16c740, v211
	v_fmamk_f32 v93, v93, 0x3e16c740, v210
	v_fmamk_f32 v125, v125, 0x3e16c740, v211
	v_fmamk_f32 v94, v94, 0x3e16c740, v210
	v_fmamk_f32 v126, v126, 0x3e16c740, v211
	v_fmamk_f32 v95, v95, 0x3e16c740, v210
	v_fmamk_f32 v127, v127, 0x3e16c740, v211
	v_fmamk_f32 v96, v96, 0x3e16c740, v210
	v_fmamk_f32 v128, v128, 0x3e16c740, v211
	v_fmamk_f32 v97, v97, 0x3e16c740, v210
	v_fmamk_f32 v129, v129, 0x3e16c740, v211
	v_exp_f32_e32 v90, v90
	v_exp_f32_e32 v122, v122
	v_exp_f32_e32 v91, v91
	v_exp_f32_e32 v123, v123
	v_exp_f32_e32 v92, v92
	v_exp_f32_e32 v124, v124
	v_exp_f32_e32 v93, v93
	v_exp_f32_e32 v125, v125
	v_exp_f32_e32 v94, v94
	v_exp_f32_e32 v126, v126
	v_exp_f32_e32 v95, v95
	v_exp_f32_e32 v127, v127
	v_exp_f32_e32 v96, v96
	v_exp_f32_e32 v128, v128
	v_exp_f32_e32 v97, v97
	v_exp_f32_e32 v129, v129
	v_cvt_pk_bf16_f32 v82, v82, v83
	v_cvt_pk_bf16_f32 v114, v114, v115
	v_cvt_pk_bf16_f32 v83, v84, v85
	v_cvt_pk_bf16_f32 v115, v116, v117
	v_cvt_pk_bf16_f32 v84, v86, v87
	v_cvt_pk_bf16_f32 v116, v118, v119
	v_cvt_pk_bf16_f32 v85, v88, v89
	v_cvt_pk_bf16_f32 v117, v120, v121
	v_fmamk_f32 v66, v66, 0x3e16c740, v210
	v_fmamk_f32 v98, v98, 0x3e16c740, v211
	v_fmamk_f32 v67, v67, 0x3e16c740, v210
	v_fmamk_f32 v99, v99, 0x3e16c740, v211
	v_fmamk_f32 v68, v68, 0x3e16c740, v210
	v_fmamk_f32 v100, v100, 0x3e16c740, v211
	v_fmamk_f32 v69, v69, 0x3e16c740, v210
	v_fmamk_f32 v101, v101, 0x3e16c740, v211
	v_fmamk_f32 v70, v70, 0x3e16c740, v210
	v_fmamk_f32 v102, v102, 0x3e16c740, v211
	v_fmamk_f32 v71, v71, 0x3e16c740, v210
	v_fmamk_f32 v103, v103, 0x3e16c740, v211
	v_fmamk_f32 v72, v72, 0x3e16c740, v210
	v_fmamk_f32 v104, v104, 0x3e16c740, v211
	v_fmamk_f32 v73, v73, 0x3e16c740, v210
	v_fmamk_f32 v105, v105, 0x3e16c740, v211
	v_exp_f32_e32 v66, v66
	v_exp_f32_e32 v98, v98
	v_exp_f32_e32 v67, v67
	v_exp_f32_e32 v99, v99
	v_exp_f32_e32 v68, v68
	v_exp_f32_e32 v100, v100
	v_exp_f32_e32 v69, v69
	v_exp_f32_e32 v101, v101
	v_exp_f32_e32 v70, v70
	v_exp_f32_e32 v102, v102
	v_exp_f32_e32 v71, v71
	v_exp_f32_e32 v103, v103
	v_exp_f32_e32 v72, v72
	v_exp_f32_e32 v104, v104
	v_exp_f32_e32 v73, v73
	v_exp_f32_e32 v105, v105
	v_cvt_pk_bf16_f32 v90, v90, v91
	v_cvt_pk_bf16_f32 v122, v122, v123
	v_cvt_pk_bf16_f32 v91, v92, v93
	v_cvt_pk_bf16_f32 v123, v124, v125
	v_cvt_pk_bf16_f32 v92, v94, v95
	v_cvt_pk_bf16_f32 v124, v126, v127
	v_cvt_pk_bf16_f32 v93, v96, v97
	v_cvt_pk_bf16_f32 v125, v128, v129
	v_fmamk_f32 v74, v74, 0x3e16c740, v210
	v_fmamk_f32 v106, v106, 0x3e16c740, v211
	v_fmamk_f32 v75, v75, 0x3e16c740, v210
	v_fmamk_f32 v107, v107, 0x3e16c740, v211
	v_fmamk_f32 v76, v76, 0x3e16c740, v210
	v_fmamk_f32 v108, v108, 0x3e16c740, v211
	v_fmamk_f32 v77, v77, 0x3e16c740, v210
	v_fmamk_f32 v109, v109, 0x3e16c740, v211
	v_fmamk_f32 v78, v78, 0x3e16c740, v210
	v_fmamk_f32 v110, v110, 0x3e16c740, v211
	v_fmamk_f32 v79, v79, 0x3e16c740, v210
	v_fmamk_f32 v111, v111, 0x3e16c740, v211
	v_fmamk_f32 v80, v80, 0x3e16c740, v210
	v_fmamk_f32 v112, v112, 0x3e16c740, v211
	v_fmamk_f32 v81, v81, 0x3e16c740, v210
	v_fmamk_f32 v113, v113, 0x3e16c740, v211
	v_exp_f32_e32 v74, v74
	v_exp_f32_e32 v106, v106
	v_exp_f32_e32 v75, v75
	v_exp_f32_e32 v107, v107
	v_exp_f32_e32 v76, v76
	v_exp_f32_e32 v108, v108
	v_exp_f32_e32 v77, v77
	v_exp_f32_e32 v109, v109
	v_exp_f32_e32 v78, v78
	v_exp_f32_e32 v110, v110
	v_exp_f32_e32 v79, v79
	v_exp_f32_e32 v111, v111
	v_exp_f32_e32 v80, v80
	v_exp_f32_e32 v112, v112
	v_exp_f32_e32 v81, v81
	v_exp_f32_e32 v113, v113
	v_cvt_pk_bf16_f32 v66, v66, v67
	v_cvt_pk_bf16_f32 v98, v98, v99
	v_cvt_pk_bf16_f32 v67, v68, v69
	v_cvt_pk_bf16_f32 v99, v100, v101
	v_cvt_pk_bf16_f32 v68, v70, v71
	v_cvt_pk_bf16_f32 v100, v102, v103
	v_cvt_pk_bf16_f32 v69, v72, v73
	v_cvt_pk_bf16_f32 v101, v104, v105
	v_cvt_pk_bf16_f32 v74, v74, v75
	v_cvt_pk_bf16_f32 v106, v106, v107
	v_cvt_pk_bf16_f32 v75, v76, v77
	v_cvt_pk_bf16_f32 v107, v108, v109
	v_cvt_pk_bf16_f32 v76, v78, v79
	v_cvt_pk_bf16_f32 v108, v110, v111
	v_cvt_pk_bf16_f32 v77, v80, v81
	v_cvt_pk_bf16_f32 v109, v112, v113
	s_setprio 2
	ds_read_b128 v[86:89], v173 offset:13312
	ds_read_b128 v[94:97], v173 offset:17920
	ds_read_b128 v[70:73], v173 offset:13344
	ds_read_b128 v[78:81], v173 offset:17952
	ds_read_b128 v[118:121], v173 offset:13376
	ds_read_b128 v[126:129], v173 offset:17984
	ds_read_b128 v[102:105], v173 offset:13408
	ds_read_b128 v[110:113], v173 offset:18016
	s_waitcnt lgkmcnt(7)
	v_mfma_f32_32x32x16_bf16 v[50:65], v[86:89], v[82:85], v[50:65]
	v_mfma_f32_32x32x16_bf16 v[18:33], v[86:89], v[114:117], v[18:33]
	s_waitcnt lgkmcnt(6)
	v_mfma_f32_32x32x16_bf16 v[34:49], v[94:97], v[82:85], v[34:49]
	v_mfma_f32_32x32x16_bf16 v[2:17], v[94:97], v[114:117], v[2:17]
	s_waitcnt lgkmcnt(5)
	v_mfma_f32_32x32x16_bf16 v[50:65], v[70:73], v[90:93], v[50:65]
	v_mfma_f32_32x32x16_bf16 v[18:33], v[70:73], v[122:125], v[18:33]
	s_waitcnt lgkmcnt(4)
	v_mfma_f32_32x32x16_bf16 v[34:49], v[78:81], v[90:93], v[34:49]
	v_mfma_f32_32x32x16_bf16 v[2:17], v[78:81], v[122:125], v[2:17]
	s_waitcnt lgkmcnt(3)
	v_mfma_f32_32x32x16_bf16 v[50:65], v[118:121], v[66:69], v[50:65]
	v_mfma_f32_32x32x16_bf16 v[18:33], v[118:121], v[98:101], v[18:33]
	s_waitcnt lgkmcnt(2)
	v_mfma_f32_32x32x16_bf16 v[34:49], v[126:129], v[66:69], v[34:49]
	v_mfma_f32_32x32x16_bf16 v[2:17], v[126:129], v[98:101], v[2:17]
	s_nop 0
	s_add_i32 s1, s1, 1
	s_add_i32 s6, s6, 64
	s_waitcnt vmcnt(0) lgkmcnt(0)
	s_barrier
; #define MFMA(a, b, c) __builtin_amdgcn_mfma_f32_32x32x16_bf16((a), (b), (c), 0, 0, 0)
; template <int DQK, bool BAND, int QT> ...
;     ...
; #pragma unroll
;         for (int qt = 0; qt < QT; ++qt) {
;           o[0][qt] = MFMA(v0, pf[qt][ks], o[0][qt]);
;           o[1][qt] = MFMA(v1, pf[qt][ks], o[1][qt]);
;         }
;       }
;     } else {
;       if (more) lstore(lds + ((it + 1) & 1) * ST);
;     }
;     __syncthreads();
	v_mfma_f32_32x32x16_bf16 v[50:65], v[102:105], v[74:77], v[50:65]
	v_mfma_f32_32x32x16_bf16 v[18:33], v[102:105], v[106:109], v[18:33]
	v_mfma_f32_32x32x16_bf16 v[34:49], v[110:113], v[74:77], v[34:49]
	v_mfma_f32_32x32x16_bf16 v[2:17], v[110:113], v[106:109], v[2:17]
	v_mfma_f32_16x16x32_bf16 v[134:137], v[130:133], v[82:85], v[134:137]
	v_mfma_f32_16x16x32_bf16 v[138:141], v[130:133], v[114:117], v[138:141]
	v_mfma_f32_16x16x32_bf16 v[134:137], v[130:133], v[90:93], v[134:137]
	v_mfma_f32_16x16x32_bf16 v[138:141], v[130:133], v[122:125], v[138:141]
	v_mfma_f32_16x16x32_bf16 v[134:137], v[130:133], v[66:69], v[134:137]
	v_mfma_f32_16x16x32_bf16 v[138:141], v[130:133], v[98:101], v[138:141]
	v_mfma_f32_16x16x32_bf16 v[134:137], v[130:133], v[74:77], v[134:137]
	v_mfma_f32_16x16x32_bf16 v[138:141], v[130:133], v[106:109], v[138:141]
	s_cmp_lg_u32 s21, s1
	s_cbranch_scc1 .Lmla_top
